# speedup vs baseline: 1.0058x; 1.0058x over previous
; __device__ __forceinline__ unsigned xb_ld(unsigned* p) { return __hip_atomic_load(p, __ATOMIC_RELAXED, __HIP_MEMORY_SCOPE_AGENT); }
; __device__ __forceinline__ unsigned xb_add(unsigned* p, unsigned v) { return __hip_atomic_fetch_add(p, v, __ATOMIC_RELAXED, __HIP_MEMORY_SCOPE_AGENT); }
; #define XB_SPIN(cond, bar) do { unsigned _sp = 0; while (cond) { __builtin_amdgcn_s_sleep(1); \
;     if ((++_sp & 255u) == 0u) { if (xb_ld(&(bar)[XB_TMO])) break; if (_sp > XB_SPIN_CAP) { atomicAdd(&(bar)[XB_TMO], 1u); break; } } } } while (0)
; __device__ __forceinline__ void xcd_barrier(const XcdBarrier& b, int tid, const unsigned gen) {
;   asm volatile("s_waitcnt vmcnt(0)" ::: "memory");
;   __syncthreads();
;   if (tid == 0) {
;     unsigned* bar = b.bar;
;     __builtin_amdgcn_s_waitcnt(0);
;     const unsigned old = xb_add(&bar[XB_XSUB(b.x)], 1u);
;     if (old + 1u == (gen + 1u) * b.nloc) {
;       __builtin_amdgcn_fence(__ATOMIC_RELEASE, "agent");
;       asm volatile("s_waitcnt vmcnt(0)" ::: "memory");
;       const unsigned og = xb_add(&bar[XB_TOP], 1u);
;       const unsigned tg = gen;
;       if (og + 1u == (tg + 1u) * b.nx) xb_add(&bar[XB_TOPGEN], 1u);
;       else XB_SPIN(xb_ld(&bar[XB_TOPGEN]) == tg, bar);
;       __builtin_amdgcn_fence(__ATOMIC_ACQUIRE, "agent");
;       xb_add(&bar[XB_XGEN(b.x)], 1u);
;     } else {
;       XB_SPIN(xb_ld(&bar[XB_XGEN(b.x)]) == gen, bar);
;       __builtin_amdgcn_fence(__ATOMIC_ACQUIRE, "agent");
;     }
.LBB0_577:
	s_and_b32 s14, s18, 0xff
	s_mov_b64 s[12:13], -1
	s_cmp_lg_u32 s14, 0
	s_mov_b64 s[16:17], -1
	s_nop 0
	s_cbranch_scc1 .LBB0_580
	v_readlane_b32 s14, v254, 21
	v_readlane_b32 s15, v254, 22
	s_nop 4
	global_load_dword v0, v1, s[14:15] sc1
	s_waitcnt vmcnt(0)
	v_cmp_eq_u32_e32 vcc, 0, v0
	s_cbranch_vccnz .LBB0_582
	s_mov_b64 s[16:17], 0
	s_mov_b64 s[14:15], -1

; __device__ __forceinline__ unsigned xb_ld(unsigned* p) { return __hip_atomic_load(p, __ATOMIC_RELAXED, __HIP_MEMORY_SCOPE_AGENT); }
; __device__ __forceinline__ unsigned xb_add(unsigned* p, unsigned v) { return __hip_atomic_fetch_add(p, v, __ATOMIC_RELAXED, __HIP_MEMORY_SCOPE_AGENT); }
; #define XB_SPIN(cond, bar) do { unsigned _sp = 0; while (cond) { __builtin_amdgcn_s_sleep(1); \
;     if ((++_sp & 255u) == 0u) { if (xb_ld(&(bar)[XB_TMO])) break; if (_sp > XB_SPIN_CAP) { atomicAdd(&(bar)[XB_TMO], 1u); break; } } } } while (0)
; __device__ __forceinline__ void xcd_barrier(const XcdBarrier& b, int tid, const unsigned gen) {
;   asm volatile("s_waitcnt vmcnt(0)" ::: "memory");
;   __syncthreads();
;   if (tid == 0) {
;     unsigned* bar = b.bar;
;     __builtin_amdgcn_s_waitcnt(0);
;     const unsigned old = xb_add(&bar[XB_XSUB(b.x)], 1u);
;     if (old + 1u == (gen + 1u) * b.nloc) {
;       __builtin_amdgcn_fence(__ATOMIC_RELEASE, "agent");
;       asm volatile("s_waitcnt vmcnt(0)" ::: "memory");
;       const unsigned og = xb_add(&bar[XB_TOP], 1u);
;       const unsigned tg = gen;
;       if (og + 1u == (tg + 1u) * b.nx) xb_add(&bar[XB_TOPGEN], 1u);
;       else XB_SPIN(xb_ld(&bar[XB_TOPGEN]) == tg, bar);
;       __builtin_amdgcn_fence(__ATOMIC_ACQUIRE, "agent");
;       xb_add(&bar[XB_XGEN(b.x)], 1u);
;     } else {
;       XB_SPIN(xb_ld(&bar[XB_XGEN(b.x)]) == gen, bar);
;       __builtin_amdgcn_fence(__ATOMIC_ACQUIRE, "agent");
;     }
.LBB0_594:
	s_and_b32 s16, s20, 0xff
	s_mov_b64 s[14:15], -1
	s_cmp_lg_u32 s16, 0
	s_mov_b64 s[18:19], -1
	s_nop 0
	s_cbranch_scc1 .LBB0_597
	v_readlane_b32 s16, v254, 21
	v_readlane_b32 s17, v254, 22
	s_nop 4
	global_load_dword v0, v1, s[16:17] sc1
	s_waitcnt vmcnt(0)
	v_cmp_eq_u32_e32 vcc, 0, v0
	s_cbranch_vccnz .LBB0_599
	s_mov_b64 s[18:19], 0
	s_mov_b64 s[16:17], -1
